# gate/up GEMM SwiGLU epilogue: serial one-temp chain -> 4-wide independent chains with v_pk_mul/v_pk_add_f32 (same per-element operations)
# baseline (speedup 1.0000x reference)
; __device__ __forceinline__ u32x4 pack8(const f32x4 a, const f32x4 b) { u32x4 w; w.x = cvt_pk_bf16(a[0], a[1]); w.y = cvt_pk_bf16(a[2], a[3]); w.z = cvt_pk_bf16(b[0], b[1]); w.w = cvt_pk_bf16(b[2], b[3]); return w; }
;     __device__ __forceinline__ void operator()(const f32x4 (&acc)[2][2][4][2], const Unit& u, int wr, int wc, int fr, int fq) const {
;         const int row0 = u.pm * BM + wr * 64 + fr, col0 = u.pn * HALF + wc * 32 + 8 * fq;
; #pragma unroll
;         for (int ai = 0; ai < 2; ++ai)
; #pragma unroll
;             for (int m = 0; m < 4; ++m) { bf16_t* rowp = H + (size_t)(row0 + ai * HALF + m * 16) * ldh + col0;
;                 f32x4 hv[2];
; #pragma unroll
;                 for (int n = 0; n < 2; ++n) { const f32x4 g = acc[ai][0][m][n], up = acc[ai][1][m][n];
; #pragma unroll
;                     for (int i = 0; i < 4; ++i) { const float e = __builtin_amdgcn_exp2f(g[i] * -1.4426950408889634f); hv[n][i] = g[i] * __builtin_amdgcn_rcpf(1.0f + e) * up[i]; } }
;                 __builtin_nontemporal_store(pack8(hv[0], hv[1]), (u32x4*)rowp); }
.LBB0_195:
	v_mov_b32_e32 v246, 1.0
	v_mov_b32_e32 v247, 1.0
	v_mov_b32_e32 v248, 0xbfb8aa3b
	v_mov_b32_e32 v249, 0xbfb8aa3b
	v_pk_mul_f32 v[250:251], v[130:131], v[248:249]
	v_pk_mul_f32 v[252:253], v[132:133], v[248:249]
	v_exp_f32_e32 v250, v250
	v_exp_f32_e32 v251, v251
	v_exp_f32_e32 v252, v252
	v_exp_f32_e32 v253, v253
	v_pk_add_f32 v[250:251], v[250:251], v[246:247]
	v_pk_add_f32 v[252:253], v[252:253], v[246:247]
	v_rcp_f32_e32 v250, v250
	v_rcp_f32_e32 v251, v251
	v_rcp_f32_e32 v252, v252
	v_rcp_f32_e32 v253, v253
	v_pk_mul_f32 v[250:251], v[130:131], v[250:251]
	v_pk_mul_f32 v[252:253], v[132:133], v[252:253]
	v_pk_mul_f32 v[236:237], v[250:251], v[126:127]
	v_pk_mul_f32 v[238:239], v[252:253], v[128:129]
	v_pk_mul_f32 v[250:251], v[122:123], v[248:249]
	v_pk_mul_f32 v[252:253], v[124:125], v[248:249]
	v_exp_f32_e32 v250, v250
	v_exp_f32_e32 v251, v251
	v_exp_f32_e32 v252, v252
	v_exp_f32_e32 v253, v253
	v_pk_add_f32 v[250:251], v[250:251], v[246:247]
	v_pk_add_f32 v[252:253], v[252:253], v[246:247]
	v_rcp_f32_e32 v250, v250
	v_rcp_f32_e32 v251, v251
	v_rcp_f32_e32 v252, v252
	v_rcp_f32_e32 v253, v253
	v_pk_mul_f32 v[250:251], v[122:123], v[250:251]
	v_pk_mul_f32 v[252:253], v[124:125], v[252:253]
	v_pk_mul_f32 v[240:241], v[250:251], v[118:119]
	v_pk_mul_f32 v[242:243], v[252:253], v[120:121]
	v_lshl_or_b32 v150, s79, 7, v146
	v_lshl_add_u32 v148, s80, 8, v1
	v_ashrrev_i32_e32 v151, 31, v150
	v_mov_b64_e32 v[144:145], s[10:11]
	v_mad_i64_i32 v[152:153], s[8:9], v148, s64, v[144:145]
	s_mov_b64 s[50:51], -1
	s_andn2_b64 vcc, exec, s[0:1]
	v_lshlrev_b64 v[118:119], 1, v[150:151]
	v_lshl_add_u64 v[124:125], v[152:153], 0, v[118:119]
	v_cvt_pk_bf16_f32 v120, v236, v237
	v_cvt_pk_bf16_f32 v121, v238, v239
	v_cvt_pk_bf16_f32 v122, v240, v241
	v_cvt_pk_bf16_f32 v123, v242, v243
	global_store_dwordx4 v[124:125], v[120:123], off nt
	s_nop 1
	v_pk_mul_f32 v[250:251], v[114:115], v[248:249]
	v_pk_mul_f32 v[252:253], v[116:117], v[248:249]
	v_exp_f32_e32 v250, v250
	v_exp_f32_e32 v251, v251
	v_exp_f32_e32 v252, v252
	v_exp_f32_e32 v253, v253
	v_pk_add_f32 v[250:251], v[250:251], v[246:247]
	v_pk_add_f32 v[252:253], v[252:253], v[246:247]
	v_rcp_f32_e32 v250, v250
	v_rcp_f32_e32 v251, v251
	v_rcp_f32_e32 v252, v252
	v_rcp_f32_e32 v253, v253
	v_pk_mul_f32 v[250:251], v[114:115], v[250:251]
	v_pk_mul_f32 v[252:253], v[116:117], v[252:253]
	v_pk_mul_f32 v[236:237], v[250:251], v[110:111]
	v_pk_mul_f32 v[238:239], v[252:253], v[112:113]
	v_pk_mul_f32 v[250:251], v[106:107], v[248:249]
	v_pk_mul_f32 v[252:253], v[108:109], v[248:249]
	v_exp_f32_e32 v250, v250
	v_exp_f32_e32 v251, v251
	v_exp_f32_e32 v252, v252
	v_exp_f32_e32 v253, v253
	v_pk_add_f32 v[250:251], v[250:251], v[246:247]
	v_pk_add_f32 v[252:253], v[252:253], v[246:247]
	v_rcp_f32_e32 v250, v250
	v_rcp_f32_e32 v251, v251
	v_rcp_f32_e32 v252, v252
	v_rcp_f32_e32 v253, v253
	v_pk_mul_f32 v[250:251], v[106:107], v[250:251]
	v_pk_mul_f32 v[252:253], v[108:109], v[252:253]
	v_pk_mul_f32 v[240:241], v[250:251], v[102:103]
	v_pk_mul_f32 v[242:243], v[252:253], v[104:105]
	v_or_b32_e32 v120, 16, v148
	v_mad_i64_i32 v[120:121], s[8:9], v120, s64, v[144:145]
	v_lshl_add_u64 v[106:107], v[120:121], 0, v[118:119]
	v_cvt_pk_bf16_f32 v102, v236, v237
	v_cvt_pk_bf16_f32 v103, v238, v239
	v_cvt_pk_bf16_f32 v104, v240, v241
	v_cvt_pk_bf16_f32 v105, v242, v243
	global_store_dwordx4 v[106:107], v[102:105], off nt
	s_nop 1
	v_pk_mul_f32 v[250:251], v[98:99], v[248:249]
	v_pk_mul_f32 v[252:253], v[100:101], v[248:249]
	v_exp_f32_e32 v250, v250
	v_exp_f32_e32 v251, v251
	v_exp_f32_e32 v252, v252
	v_exp_f32_e32 v253, v253
	v_pk_add_f32 v[250:251], v[250:251], v[246:247]
	v_pk_add_f32 v[252:253], v[252:253], v[246:247]
	v_rcp_f32_e32 v250, v250
	v_rcp_f32_e32 v251, v251
	v_rcp_f32_e32 v252, v252
	v_rcp_f32_e32 v253, v253
	v_pk_mul_f32 v[250:251], v[98:99], v[250:251]
	v_pk_mul_f32 v[252:253], v[100:101], v[252:253]
	v_pk_mul_f32 v[236:237], v[250:251], v[94:95]
	v_pk_mul_f32 v[238:239], v[252:253], v[96:97]
	v_pk_mul_f32 v[250:251], v[90:91], v[248:249]
	v_pk_mul_f32 v[252:253], v[92:93], v[248:249]
	v_exp_f32_e32 v250, v250
	v_exp_f32_e32 v251, v251
	v_exp_f32_e32 v252, v252
	v_exp_f32_e32 v253, v253
	v_pk_add_f32 v[250:251], v[250:251], v[246:247]
	v_pk_add_f32 v[252:253], v[252:253], v[246:247]
	v_rcp_f32_e32 v250, v250
	v_rcp_f32_e32 v251, v251
	v_rcp_f32_e32 v252, v252
	v_rcp_f32_e32 v253, v253
	v_pk_mul_f32 v[250:251], v[90:91], v[250:251]
	v_pk_mul_f32 v[252:253], v[92:93], v[252:253]
	v_pk_mul_f32 v[240:241], v[250:251], v[86:87]
	v_pk_mul_f32 v[242:243], v[252:253], v[88:89]
	v_or_b32_e32 v102, 32, v148
	v_mad_i64_i32 v[102:103], s[8:9], v102, s64, v[144:145]
	v_lshl_add_u64 v[90:91], v[102:103], 0, v[118:119]
	v_cvt_pk_bf16_f32 v86, v236, v237
	v_cvt_pk_bf16_f32 v87, v238, v239
	v_cvt_pk_bf16_f32 v88, v240, v241
	v_cvt_pk_bf16_f32 v89, v242, v243
	global_store_dwordx4 v[90:91], v[86:89], off nt
	s_nop 1
	v_pk_mul_f32 v[250:251], v[82:83], v[248:249]
	v_pk_mul_f32 v[252:253], v[84:85], v[248:249]
	v_exp_f32_e32 v250, v250
	v_exp_f32_e32 v251, v251
	v_exp_f32_e32 v252, v252
	v_exp_f32_e32 v253, v253
	v_pk_add_f32 v[250:251], v[250:251], v[246:247]
	v_pk_add_f32 v[252:253], v[252:253], v[246:247]
	v_rcp_f32_e32 v250, v250
	v_rcp_f32_e32 v251, v251
	v_rcp_f32_e32 v252, v252
	v_rcp_f32_e32 v253, v253
	v_pk_mul_f32 v[250:251], v[82:83], v[250:251]
	v_pk_mul_f32 v[252:253], v[84:85], v[252:253]
	v_pk_mul_f32 v[236:237], v[250:251], v[78:79]
	v_pk_mul_f32 v[238:239], v[252:253], v[80:81]
	v_pk_mul_f32 v[250:251], v[74:75], v[248:249]
	v_pk_mul_f32 v[252:253], v[76:77], v[248:249]
	v_exp_f32_e32 v250, v250
; __device__ __forceinline__ u32x4 pack8(const f32x4 a, const f32x4 b) { u32x4 w; w.x = cvt_pk_bf16(a[0], a[1]); w.y = cvt_pk_bf16(a[2], a[3]); w.z = cvt_pk_bf16(b[0], b[1]); w.w = cvt_pk_bf16(b[2], b[3]); return w; }
;     __device__ __forceinline__ void operator()(const f32x4 (&acc)[2][2][4][2], const Unit& u, int wr, int wc, int fr, int fq) const {
;         const int row0 = u.pm * BM + wr * 64 + fr, col0 = u.pn * HALF + wc * 32 + 8 * fq;
; #pragma unroll
;         for (int ai = 0; ai < 2; ++ai)
; #pragma unroll
;             for (int m = 0; m < 4; ++m) { bf16_t* rowp = H + (size_t)(row0 + ai * HALF + m * 16) * ldh + col0;
;                 f32x4 hv[2];
; #pragma unroll
;                 for (int n = 0; n < 2; ++n) { const f32x4 g = acc[ai][0][m][n], up = acc[ai][1][m][n];
; #pragma unroll
;                     for (int i = 0; i < 4; ++i) { const float e = __builtin_amdgcn_exp2f(g[i] * -1.4426950408889634f); hv[n][i] = g[i] * __builtin_amdgcn_rcpf(1.0f + e) * up[i]; } }
;                 __builtin_nontemporal_store(pack8(hv[0], hv[1]), (u32x4*)rowp); }
	v_exp_f32_e32 v251, v251
	v_exp_f32_e32 v252, v252
	v_exp_f32_e32 v253, v253
	v_pk_add_f32 v[250:251], v[250:251], v[246:247]
	v_pk_add_f32 v[252:253], v[252:253], v[246:247]
	v_rcp_f32_e32 v250, v250
	v_rcp_f32_e32 v251, v251
	v_rcp_f32_e32 v252, v252
	v_rcp_f32_e32 v253, v253
	v_pk_mul_f32 v[250:251], v[74:75], v[250:251]
	v_pk_mul_f32 v[252:253], v[76:77], v[252:253]
	v_pk_mul_f32 v[240:241], v[250:251], v[70:71]
	v_pk_mul_f32 v[242:243], v[252:253], v[72:73]
	v_or_b32_e32 v86, 48, v148
	v_mad_i64_i32 v[86:87], s[8:9], v86, s64, v[144:145]
	v_lshl_add_u64 v[74:75], v[86:87], 0, v[118:119]
	v_cvt_pk_bf16_f32 v70, v236, v237
	v_cvt_pk_bf16_f32 v71, v238, v239
	v_cvt_pk_bf16_f32 v72, v240, v241
	v_cvt_pk_bf16_f32 v73, v242, v243
	global_store_dwordx4 v[74:75], v[70:73], off nt
	s_nop 1
	v_pk_mul_f32 v[250:251], v[66:67], v[248:249]
	v_pk_mul_f32 v[252:253], v[68:69], v[248:249]
	v_exp_f32_e32 v250, v250
	v_exp_f32_e32 v251, v251
	v_exp_f32_e32 v252, v252
	v_exp_f32_e32 v253, v253
	v_pk_add_f32 v[250:251], v[250:251], v[246:247]
	v_pk_add_f32 v[252:253], v[252:253], v[246:247]
	v_rcp_f32_e32 v250, v250
	v_rcp_f32_e32 v251, v251
	v_rcp_f32_e32 v252, v252
	v_rcp_f32_e32 v253, v253
	v_pk_mul_f32 v[250:251], v[66:67], v[250:251]
	v_pk_mul_f32 v[252:253], v[68:69], v[252:253]
	v_pk_mul_f32 v[236:237], v[250:251], v[62:63]
	v_pk_mul_f32 v[238:239], v[252:253], v[64:65]
	v_pk_mul_f32 v[250:251], v[58:59], v[248:249]
	v_pk_mul_f32 v[252:253], v[60:61], v[248:249]
	v_exp_f32_e32 v250, v250
	v_exp_f32_e32 v251, v251
	v_exp_f32_e32 v252, v252
	v_exp_f32_e32 v253, v253
	v_pk_add_f32 v[250:251], v[250:251], v[246:247]
	v_pk_add_f32 v[252:253], v[252:253], v[246:247]
	v_rcp_f32_e32 v250, v250
	v_rcp_f32_e32 v251, v251
	v_rcp_f32_e32 v252, v252
	v_rcp_f32_e32 v253, v253
	v_pk_mul_f32 v[250:251], v[58:59], v[250:251]
	v_pk_mul_f32 v[252:253], v[60:61], v[252:253]
	v_pk_mul_f32 v[240:241], v[250:251], v[54:55]
	v_pk_mul_f32 v[242:243], v[252:253], v[56:57]
	v_add_u32_e32 v70, 0x80, v148
	v_mad_i64_i32 v[70:71], s[8:9], v70, s64, v[144:145]
	v_lshl_add_u64 v[58:59], v[70:71], 0, v[118:119]
	v_cvt_pk_bf16_f32 v54, v236, v237
	v_cvt_pk_bf16_f32 v55, v238, v239
	v_cvt_pk_bf16_f32 v56, v240, v241
	v_cvt_pk_bf16_f32 v57, v242, v243
	global_store_dwordx4 v[58:59], v[54:57], off nt
	s_nop 1
	v_pk_mul_f32 v[250:251], v[50:51], v[248:249]
	v_pk_mul_f32 v[252:253], v[52:53], v[248:249]
	v_exp_f32_e32 v250, v250
	v_exp_f32_e32 v251, v251
	v_exp_f32_e32 v252, v252
	v_exp_f32_e32 v253, v253
	v_pk_add_f32 v[250:251], v[250:251], v[246:247]
	v_pk_add_f32 v[252:253], v[252:253], v[246:247]
	v_rcp_f32_e32 v250, v250
	v_rcp_f32_e32 v251, v251
	v_rcp_f32_e32 v252, v252
	v_rcp_f32_e32 v253, v253
	v_pk_mul_f32 v[250:251], v[50:51], v[250:251]
	v_pk_mul_f32 v[252:253], v[52:53], v[252:253]
	v_pk_mul_f32 v[236:237], v[250:251], v[46:47]
	v_pk_mul_f32 v[238:239], v[252:253], v[48:49]
	v_pk_mul_f32 v[250:251], v[42:43], v[248:249]
	v_pk_mul_f32 v[252:253], v[44:45], v[248:249]
	v_exp_f32_e32 v250, v250
	v_exp_f32_e32 v251, v251
	v_exp_f32_e32 v252, v252
	v_exp_f32_e32 v253, v253
	v_pk_add_f32 v[250:251], v[250:251], v[246:247]
	v_pk_add_f32 v[252:253], v[252:253], v[246:247]
	v_rcp_f32_e32 v250, v250
	v_rcp_f32_e32 v251, v251
	v_rcp_f32_e32 v252, v252
	v_rcp_f32_e32 v253, v253
	v_pk_mul_f32 v[250:251], v[42:43], v[250:251]
	v_pk_mul_f32 v[252:253], v[44:45], v[252:253]
	v_pk_mul_f32 v[240:241], v[250:251], v[38:39]
	v_pk_mul_f32 v[242:243], v[252:253], v[40:41]
	v_add_u32_e32 v54, 0x90, v148
	v_mad_i64_i32 v[54:55], s[8:9], v54, s64, v[144:145]
	v_lshl_add_u64 v[42:43], v[54:55], 0, v[118:119]
	v_cvt_pk_bf16_f32 v38, v236, v237
	v_cvt_pk_bf16_f32 v39, v238, v239
	v_cvt_pk_bf16_f32 v40, v240, v241
	v_cvt_pk_bf16_f32 v41, v242, v243
	global_store_dwordx4 v[42:43], v[38:41], off nt
	s_nop 1
	v_pk_mul_f32 v[250:251], v[34:35], v[248:249]
	v_pk_mul_f32 v[252:253], v[36:37], v[248:249]
	v_exp_f32_e32 v250, v250
	v_exp_f32_e32 v251, v251
	v_exp_f32_e32 v252, v252
	v_exp_f32_e32 v253, v253
	v_pk_add_f32 v[250:251], v[250:251], v[246:247]
	v_pk_add_f32 v[252:253], v[252:253], v[246:247]
	v_rcp_f32_e32 v250, v250
	v_rcp_f32_e32 v251, v251
	v_rcp_f32_e32 v252, v252
	v_rcp_f32_e32 v253, v253
	v_pk_mul_f32 v[250:251], v[34:35], v[250:251]
	v_pk_mul_f32 v[252:253], v[36:37], v[252:253]
	v_pk_mul_f32 v[236:237], v[250:251], v[30:31]
	v_pk_mul_f32 v[238:239], v[252:253], v[32:33]
	v_pk_mul_f32 v[250:251], v[26:27], v[248:249]
	v_pk_mul_f32 v[252:253], v[28:29], v[248:249]
	v_exp_f32_e32 v250, v250
	v_exp_f32_e32 v251, v251
	v_exp_f32_e32 v252, v252
	v_exp_f32_e32 v253, v253
	v_pk_add_f32 v[250:251], v[250:251], v[246:247]
	v_pk_add_f32 v[252:253], v[252:253], v[246:247]
	v_rcp_f32_e32 v250, v250
	v_rcp_f32_e32 v251, v251
	v_rcp_f32_e32 v252, v252
	v_rcp_f32_e32 v253, v253
	v_pk_mul_f32 v[250:251], v[26:27], v[250:251]
	v_pk_mul_f32 v[252:253], v[28:29], v[252:253]
	v_pk_mul_f32 v[240:241], v[250:251], v[22:23]
	v_pk_mul_f32 v[242:243], v[252:253], v[24:25]
	v_add_u32_e32 v38, 0xa0, v148
	v_mad_i64_i32 v[38:39], s[8:9], v38, s64, v[144:145]
	v_lshl_add_u64 v[26:27], v[38:39], 0, v[118:119]
	v_cvt_pk_bf16_f32 v22, v236, v237
	v_cvt_pk_bf16_f32 v23, v238, v239
	v_cvt_pk_bf16_f32 v24, v240, v241
	v_cvt_pk_bf16_f32 v25, v242, v243
	global_store_dwordx4 v[26:27], v[22:25], off nt
	s_nop 1
	v_pk_mul_f32 v[250:251], v[18:19], v[248:249]
	v_pk_mul_f32 v[252:253], v[20:21], v[248:249]
	v_exp_f32_e32 v250, v250
	v_exp_f32_e32 v251, v251
	v_exp_f32_e32 v252, v252
	v_exp_f32_e32 v253, v253
	v_pk_add_f32 v[250:251], v[250:251], v[246:247]
	v_pk_add_f32 v[252:253], v[252:253], v[246:247]
	v_rcp_f32_e32 v250, v250
	v_rcp_f32_e32 v251, v251
	v_rcp_f32_e32 v252, v252
	v_rcp_f32_e32 v253, v253
	v_pk_mul_f32 v[250:251], v[18:19], v[250:251]
	v_pk_mul_f32 v[252:253], v[20:21], v[252:253]
	v_pk_mul_f32 v[236:237], v[250:251], v[10:11]
	v_pk_mul_f32 v[238:239], v[252:253], v[12:13]
	v_pk_mul_f32 v[250:251], v[6:7], v[248:249]
	v_pk_mul_f32 v[252:253], v[8:9], v[248:249]
	v_exp_f32_e32 v250, v250
	v_exp_f32_e32 v251, v251
	v_exp_f32_e32 v252, v252
	v_exp_f32_e32 v253, v253
	v_pk_add_f32 v[250:251], v[250:251], v[246:247]
	v_pk_add_f32 v[252:253], v[252:253], v[246:247]
	v_rcp_f32_e32 v250, v250
	v_rcp_f32_e32 v251, v251
	v_rcp_f32_e32 v252, v252
	v_rcp_f32_e32 v253, v253
	v_pk_mul_f32 v[250:251], v[6:7], v[250:251]
	v_pk_mul_f32 v[252:253], v[8:9], v[252:253]
	v_pk_mul_f32 v[240:241], v[250:251], v[2:3]
	v_pk_mul_f32 v[242:243], v[252:253], v[4:5]
	v_add_u32_e32 v22, 0xb0, v148
	v_mad_i64_i32 v[22:23], s[8:9], v22, s64, v[144:145]
	v_lshl_add_u64 v[6:7], v[22:23], 0, v[118:119]
	v_cvt_pk_bf16_f32 v2, v236, v237
	v_cvt_pk_bf16_f32 v3, v238, v239
	v_cvt_pk_bf16_f32 v4, v240, v241
	v_cvt_pk_bf16_f32 v5, v242, v243
	global_store_dwordx4 v[6:7], v[2:5], off nt
	s_nop 1
	s_cbranch_vccnz .LBB0_188
	s_andn2_b64 vcc, exec, s[2:3]
	s_cbranch_vccnz .LBB0_187
	s_barrier
	s_branch .LBB0_187
